# S5 chain: MFMA wave de-serialised (distinct acc regs, LDS reads hoisted), scan wave exact vmcnt(3) ring waits + inline-asm pads removed; gated-delta: exact vmcnt(6) at g/beta hand-off
# speedup vs baseline: 1.0608x; 1.0061x over previous
.LBB0_373:
	ds_read_b128 v[96:99], v83 offset:5120
	ds_read_b128 v[100:103], v83 offset:5136
	ds_read_b128 v[104:107], v83
	ds_read_b128 v[108:111], v83 offset:16
	ds_read_b128 v[112:115], v83 offset:32
	ds_read_b128 v[116:119], v83 offset:48
	ds_read_b128 v[120:123], v83 offset:5152
	ds_read_b128 v[124:127], v83 offset:5168
	s_waitcnt lgkmcnt(7)
	v_fma_f32 v96, v71, v94, v96
	s_waitcnt lgkmcnt(5)
	v_fma_f32 v95, v75, v93, v104
	s_waitcnt lgkmcnt(0)
	s_cmpk_gt_u32 s9, 0x10b
	v_fma_f32 v94, v70, v94, v95
	v_fma_f32 v93, v70, v93, v96
	s_mov_b32 s10, s9
	v_fma_f32 v96, v75, v93, v105
	v_cvt_pk_bf16_f32 v95, v94, v93
	v_fma_f32 v97, v71, v94, v97
	v_fma_f32 v94, v70, v94, v96
	v_fma_f32 v93, v70, v93, v97
	v_cvt_pk_bf16_f32 v96, v94, v93
	ds_write2_b32 v89, v95, v96 offset1:68
	v_fma_f32 v96, v71, v94, v98
	v_fma_f32 v95, v75, v93, v106
	v_fma_f32 v94, v70, v94, v95
	v_fma_f32 v93, v70, v93, v96
	v_fma_f32 v96, v75, v93, v107
	v_cvt_pk_bf16_f32 v95, v94, v93
	v_fma_f32 v97, v71, v94, v99
	v_fma_f32 v94, v70, v94, v96
	v_fma_f32 v93, v70, v93, v97
	v_cvt_pk_bf16_f32 v96, v94, v93
	ds_write2_b32 v89, v95, v96 offset0:136 offset1:204
	s_waitcnt lgkmcnt(6)
	v_fma_f32 v89, v75, v93, v108
	v_fma_f32 v95, v71, v94, v100
	v_fma_f32 v89, v70, v94, v89
	v_fma_f32 v93, v70, v93, v95
	v_fma_f32 v95, v75, v93, v109
	v_cvt_pk_bf16_f32 v94, v89, v93
	v_fma_f32 v96, v71, v89, v101
	v_fma_f32 v89, v70, v89, v95
	v_fma_f32 v93, v70, v93, v96
	v_cvt_pk_bf16_f32 v95, v89, v93
	ds_write2_b32 v90, v94, v95 offset0:16 offset1:84
	v_fma_f32 v95, v71, v89, v102
	v_fma_f32 v94, v75, v93, v110
	v_fma_f32 v89, v70, v89, v94
	v_fma_f32 v93, v70, v93, v95
	v_fma_f32 v95, v75, v93, v111
	v_cvt_pk_bf16_f32 v94, v89, v93
	v_fma_f32 v96, v71, v89, v103
	v_fma_f32 v89, v70, v89, v95
	v_fma_f32 v93, v70, v93, v96
	v_cvt_pk_bf16_f32 v95, v89, v93
	ds_write2_b32 v90, v94, v95 offset0:152 offset1:220
	s_waitcnt lgkmcnt(7)
	v_fma_f32 v90, v75, v93, v112
	s_waitcnt lgkmcnt(5)
	v_fma_f32 v94, v71, v89, v120
	v_fma_f32 v89, v70, v89, v90
	v_fma_f32 v90, v70, v93, v94
	v_fma_f32 v94, v75, v90, v113
	v_cvt_pk_bf16_f32 v93, v89, v90
	v_fma_f32 v95, v71, v89, v121
	v_fma_f32 v89, v70, v89, v94
	v_fma_f32 v90, v70, v90, v95
	v_cvt_pk_bf16_f32 v94, v89, v90
	ds_write2_b32 v92, v93, v94 offset0:32 offset1:100
	v_fma_f32 v94, v71, v89, v122
	v_fma_f32 v93, v75, v90, v114
	v_fma_f32 v89, v70, v89, v93
	v_fma_f32 v90, v70, v90, v94
	v_fma_f32 v94, v75, v90, v115
	v_cvt_pk_bf16_f32 v93, v89, v90
	v_fma_f32 v95, v71, v89, v123
	v_fma_f32 v89, v70, v89, v94
	v_fma_f32 v90, v70, v90, v95
	v_cvt_pk_bf16_f32 v94, v89, v90
	ds_write2_b32 v92, v93, v94 offset0:168 offset1:236
	s_waitcnt lgkmcnt(6)
	v_fma_f32 v93, v71, v89, v124
	v_fma_f32 v92, v75, v90, v116
	v_fma_f32 v89, v70, v89, v92
	v_fma_f32 v90, v70, v90, v93
	v_fma_f32 v93, v75, v90, v117
	v_cvt_pk_bf16_f32 v92, v89, v90
	v_fma_f32 v94, v71, v89, v125
	v_fma_f32 v89, v70, v89, v93
	v_fma_f32 v90, v70, v90, v94
	v_cvt_pk_bf16_f32 v93, v89, v90
	ds_write2_b32 v91, v92, v93 offset0:48 offset1:116
	v_fma_f32 v93, v71, v89, v126
	v_fma_f32 v92, v75, v90, v118
	v_fma_f32 v89, v70, v89, v92
	v_fma_f32 v90, v70, v90, v93
	v_fma_f32 v93, v75, v90, v119
	v_cvt_pk_bf16_f32 v92, v89, v90
	v_fma_f32 v94, v71, v89, v127
	v_fma_f32 v89, v70, v89, v93
	v_fma_f32 v90, v70, v90, v94
	v_cvt_pk_bf16_f32 v93, v89, v90
	ds_write2_b32 v91, v92, v93 offset0:184 offset1:252
	s_waitcnt lgkmcnt(0)
	s_barrier
	s_cbranch_scc1 .LBB0_385
.LBB0_374:
	s_and_saveexec_b64 s[4:5], vcc
	s_cbranch_execz .LBB0_376
	v_add_u32_e32 v75, v84, v85
	s_waitcnt vmcnt(3)
	ds_write_b128 v75, v[52:55] offset:29696
.LBB0_376:
	s_or_b64 exec, exec, s[4:5]
	s_add_i32 s9, s10, 4
	s_min_u32 s4, s9, 0x10a
	s_lshl_b32 s4, s4, 4
	s_cmp_lt_u32 s9, 11
	s_movk_i32 s5, 0xff50
	s_movk_i32 s11, 0xaf
	s_cselect_b32 s5, 0x50, s5
	s_cselect_b32 s11, s11, 0x10af
	s_cselect_b32 s12, s8, s2
	s_add_i32 s13, s4, s5
	s_sub_i32 s11, s11, s4
	s_and_b64 s[4:5], s[6:7], exec
	s_cselect_b32 s4, s13, s11
	s_add_i32 s4, s4, s12
	s_waitcnt vmcnt(3)
	v_add_u32_e32 v52, s4, v74
	v_mad_u32_u24 v52, v52, s63, v82
	v_ashrrev_i32_e32 v53, 31, v52
	v_lshl_add_u64 v[52:53], v[52:53], 1, s[82:83]
	global_load_dwordx4 v[52:55], v[52:53], off
	s_add_i32 s4, s10, 3
	s_cmpk_gt_u32 s4, 0x10f
	v_xor_b32_e32 v75, 0x80000000, v71
	v_add_u32_e32 v88, 0x6000, v87
	v_add_u32_e32 v86, 0x6200, v87
	v_add_u32_e32 v81, 0x6400, v87
	v_add_u32_e32 v80, 0x6600, v87
	v_add_u32_e32 v79, 0x6800, v87
	v_add_u32_e32 v78, 0x6a00, v87
	v_add_u32_e32 v77, 0x6c00, v87
	v_add_u32_e32 v76, 0x6e00, v87
	s_cbranch_scc1 .LBB0_378
	ds_read_b128 v[92:95], v83 offset:15360
	ds_read_b128 v[96:99], v83 offset:15376
	ds_read_b128 v[100:103], v83 offset:10240
	ds_read_b128 v[104:107], v83 offset:10256
	ds_read_b128 v[108:111], v83 offset:10272
	ds_read_b128 v[112:115], v83 offset:10288
	ds_read_b128 v[116:119], v83 offset:15392
	ds_read_b128 v[120:123], v83 offset:15408
	s_waitcnt lgkmcnt(7)
	v_fma_f32 v92, v71, v89, v92
	s_waitcnt lgkmcnt(5)
	v_fma_f32 v91, v75, v90, v100
	s_waitcnt lgkmcnt(0)
	v_fma_f32 v89, v70, v89, v91
	v_fma_f32 v90, v70, v90, v92
	v_fma_f32 v92, v75, v90, v101
	v_cvt_pk_bf16_f32 v91, v89, v90
	v_fma_f32 v93, v71, v89, v93
	v_fma_f32 v89, v70, v89, v92
	v_fma_f32 v90, v70, v90, v93
	v_cvt_pk_bf16_f32 v92, v89, v90
	ds_write2_b32 v88, v91, v92 offset0:64 offset1:132
	v_fma_f32 v92, v71, v89, v94
	v_fma_f32 v91, v75, v90, v102
	v_fma_f32 v89, v70, v89, v91
	v_fma_f32 v90, v70, v90, v92
	v_fma_f32 v92, v75, v90, v103
	v_cvt_pk_bf16_f32 v91, v89, v90
	v_fma_f32 v93, v71, v89, v95
	v_fma_f32 v89, v70, v89, v92
	v_fma_f32 v90, v70, v90, v93
	v_cvt_pk_bf16_f32 v92, v89, v90
	ds_write2_b32 v86, v91, v92 offset0:72 offset1:140
	v_fma_f32 v92, v71, v89, v96
	s_waitcnt lgkmcnt(6)
	v_fma_f32 v91, v75, v90, v104
	v_fma_f32 v89, v70, v89, v91
	v_fma_f32 v90, v70, v90, v92
	v_fma_f32 v92, v75, v90, v105
	v_cvt_pk_bf16_f32 v91, v89, v90
	v_fma_f32 v93, v71, v89, v97
	v_fma_f32 v89, v70, v89, v92
	v_fma_f32 v90, v70, v90, v93
	v_cvt_pk_bf16_f32 v92, v89, v90
	ds_write2_b32 v81, v91, v92 offset0:80 offset1:148
	v_fma_f32 v92, v71, v89, v98
	v_fma_f32 v91, v75, v90, v106
	v_fma_f32 v89, v70, v89, v91
	v_fma_f32 v90, v70, v90, v92
	v_fma_f32 v92, v75, v90, v107
	v_cvt_pk_bf16_f32 v91, v89, v90
	v_fma_f32 v93, v71, v89, v99
	v_fma_f32 v89, v70, v89, v92
	v_fma_f32 v90, v70, v90, v93
	v_cvt_pk_bf16_f32 v92, v89, v90
	ds_write2_b32 v80, v91, v92 offset0:88 offset1:156
	s_waitcnt lgkmcnt(5)
	v_fma_f32 v92, v71, v89, v116
	v_fma_f32 v91, v75, v90, v108
	v_fma_f32 v89, v70, v89, v91
	v_fma_f32 v90, v70, v90, v92
	v_fma_f32 v92, v75, v90, v109
	v_cvt_pk_bf16_f32 v91, v89, v90
	v_fma_f32 v93, v71, v89, v117
	v_fma_f32 v89, v70, v89, v92
	v_fma_f32 v90, v70, v90, v93
	v_cvt_pk_bf16_f32 v92, v89, v90
	ds_write2_b32 v79, v91, v92 offset0:96 offset1:164
	v_fma_f32 v92, v71, v89, v118
	v_fma_f32 v91, v75, v90, v110
	v_fma_f32 v89, v70, v89, v91
	v_fma_f32 v90, v70, v90, v92
	v_fma_f32 v92, v75, v90, v111
	v_cvt_pk_bf16_f32 v91, v89, v90
	v_fma_f32 v93, v71, v89, v119
	v_fma_f32 v89, v70, v89, v92
	v_fma_f32 v90, v70, v90, v93
	v_cvt_pk_bf16_f32 v92, v89, v90
	ds_write2_b32 v78, v91, v92 offset0:104 offset1:172
	s_waitcnt lgkmcnt(6)
	v_fma_f32 v92, v71, v89, v120
	v_fma_f32 v91, v75, v90, v112
	v_fma_f32 v89, v70, v89, v91
	v_fma_f32 v90, v70, v90, v92
	v_fma_f32 v92, v75, v90, v113
	v_cvt_pk_bf16_f32 v91, v89, v90
	v_fma_f32 v93, v71, v89, v121
	v_fma_f32 v89, v70, v89, v92
	v_fma_f32 v90, v70, v90, v93
	v_cvt_pk_bf16_f32 v92, v89, v90
	ds_write2_b32 v77, v91, v92 offset0:112 offset1:180
	v_fma_f32 v92, v71, v89, v122
	v_fma_f32 v91, v75, v90, v114
	v_fma_f32 v89, v70, v89, v91
	v_fma_f32 v90, v70, v90, v92
	v_fma_f32 v92, v75, v90, v115
	v_cvt_pk_bf16_f32 v91, v89, v90
	v_fma_f32 v93, v71, v89, v123
	v_fma_f32 v89, v70, v89, v92
	v_fma_f32 v90, v70, v90, v93
	v_cvt_pk_bf16_f32 v92, v89, v90
	ds_write2_b32 v76, v91, v92 offset0:120 offset1:188
.LBB0_378:
	s_waitcnt lgkmcnt(0)
	s_barrier
	s_and_saveexec_b64 s[4:5], vcc
	v_add_u32_e32 v91, v84, v85
	s_waitcnt vmcnt(3)
	ds_write_b128 v91, v[56:59] offset:29184
	s_or_b64 exec, exec, s[4:5]
	s_add_i32 s4, s10, 5
	s_min_u32 s5, s4, 0x10a
	s_lshl_b32 s5, s5, 4
	s_cmp_lt_u32 s4, 11
	s_movk_i32 s4, 0xff50
	s_movk_i32 s11, 0xaf
	s_cselect_b32 s4, 0x50, s4
	s_cselect_b32 s11, s11, 0x10af
	s_cselect_b32 s12, s8, s2
	s_add_i32 s13, s5, s4
	s_sub_i32 s11, s11, s5
	s_and_b64 s[4:5], s[6:7], exec
	s_cselect_b32 s4, s13, s11
	s_add_i32 s4, s4, s12
	v_add_u32_e32 v56, s4, v74
	v_mad_u32_u24 v56, v56, s63, v82
	v_ashrrev_i32_e32 v57, 31, v56
	v_lshl_add_u64 v[56:57], v[56:57], 1, s[82:83]
	global_load_dwordx4 v[56:59], v[56:57], off
	ds_read_b128 v[92:95], v83 offset:5120
	ds_read_b128 v[96:99], v83 offset:5136
	ds_read_b128 v[100:103], v83
	ds_read_b128 v[104:107], v83 offset:16
	ds_read_b128 v[108:111], v83 offset:32
	ds_read_b128 v[112:115], v83 offset:48
	ds_read_b128 v[116:119], v83 offset:5152
	ds_read_b128 v[120:123], v83 offset:5168
	s_waitcnt lgkmcnt(7)
	v_fma_f32 v92, v71, v89, v92
	s_waitcnt lgkmcnt(5)
	v_fma_f32 v91, v75, v90, v100
	s_waitcnt lgkmcnt(0)
	v_fma_f32 v89, v70, v89, v91
	v_fma_f32 v90, v70, v90, v92
	v_fma_f32 v92, v75, v90, v101
	v_fma_f32 v93, v71, v89, v93
	v_cvt_pk_bf16_f32 v91, v89, v90
	v_fma_f32 v92, v70, v89, v92
	v_fma_f32 v90, v70, v90, v93
	v_add_u32_e32 v89, 0x5000, v87
	v_cvt_pk_bf16_f32 v93, v92, v90
	ds_write2_b32 v89, v91, v93 offset1:68
	v_fma_f32 v91, v75, v90, v102
	v_fma_f32 v93, v71, v92, v94
	v_fma_f32 v91, v70, v92, v91
	v_fma_f32 v90, v70, v90, v93
	v_fma_f32 v93, v75, v90, v103
	v_cvt_pk_bf16_f32 v92, v91, v90
	v_fma_f32 v94, v71, v91, v95
	v_fma_f32 v91, v70, v91, v93
	v_fma_f32 v90, v70, v90, v94
	v_cvt_pk_bf16_f32 v93, v91, v90
	ds_write2_b32 v89, v92, v93 offset0:136 offset1:204
	v_fma_f32 v93, v71, v91, v96
	s_waitcnt lgkmcnt(6)
	v_fma_f32 v92, v75, v90, v104
	v_fma_f32 v91, v70, v91, v92
	v_fma_f32 v90, v70, v90, v93
	v_fma_f32 v93, v75, v90, v105
	v_fma_f32 v94, v71, v91, v97
	v_cvt_pk_bf16_f32 v92, v91, v90
	v_fma_f32 v91, v70, v91, v93
	v_fma_f32 v93, v70, v90, v94
	v_add_u32_e32 v90, 0x5400, v87
	v_cvt_pk_bf16_f32 v94, v91, v93
	ds_write2_b32 v90, v92, v94 offset0:16 offset1:84
	v_fma_f32 v92, v75, v93, v106
	v_fma_f32 v94, v71, v91, v98
	v_fma_f32 v91, v70, v91, v92
	v_fma_f32 v92, v70, v93, v94
	v_fma_f32 v94, v75, v92, v107
	v_cvt_pk_bf16_f32 v93, v91, v92
	v_fma_f32 v95, v71, v91, v99
	v_fma_f32 v91, v70, v91, v94
	v_fma_f32 v92, v70, v92, v95
	v_cvt_pk_bf16_f32 v94, v91, v92
	ds_write2_b32 v90, v93, v94 offset0:152 offset1:220
	s_waitcnt lgkmcnt(5)
	v_fma_f32 v94, v71, v91, v116
	v_fma_f32 v93, v75, v92, v108
	v_fma_f32 v91, v70, v91, v93
	v_fma_f32 v92, v70, v92, v94
	v_fma_f32 v94, v75, v92, v109
	v_fma_f32 v95, v71, v91, v117
	v_cvt_pk_bf16_f32 v93, v91, v92
	v_fma_f32 v91, v70, v91, v94
	v_fma_f32 v94, v70, v92, v95
	v_add_u32_e32 v92, 0x5800, v87
	v_cvt_pk_bf16_f32 v95, v91, v94
	ds_write2_b32 v92, v93, v95 offset0:32 offset1:100
	v_fma_f32 v93, v75, v94, v110
	v_fma_f32 v95, v71, v91, v118
	v_fma_f32 v91, v70, v91, v93
	v_fma_f32 v93, v70, v94, v95
	v_fma_f32 v95, v75, v93, v111
	v_cvt_pk_bf16_f32 v94, v91, v93
	v_fma_f32 v96, v71, v91, v119
	v_fma_f32 v91, v70, v91, v95
	v_fma_f32 v93, v70, v93, v96
	v_cvt_pk_bf16_f32 v95, v91, v93
	ds_write2_b32 v92, v94, v95 offset0:168 offset1:236
	s_waitcnt lgkmcnt(6)
	v_fma_f32 v95, v71, v91, v120
	v_fma_f32 v94, v75, v93, v112
	v_fma_f32 v91, v70, v91, v94
	v_fma_f32 v93, v70, v93, v95
	v_fma_f32 v95, v75, v93, v113
	v_fma_f32 v96, v71, v91, v121
	v_cvt_pk_bf16_f32 v94, v91, v93
	v_fma_f32 v95, v70, v91, v95
	v_fma_f32 v93, v70, v93, v96
	v_add_u32_e32 v91, 0x5c00, v87
	v_cvt_pk_bf16_f32 v96, v95, v93
	ds_write2_b32 v91, v94, v96 offset0:48 offset1:116
	v_fma_f32 v94, v75, v93, v114
	v_fma_f32 v96, v71, v95, v122
	v_fma_f32 v94, v70, v95, v94
	v_fma_f32 v93, v70, v93, v96
	v_fma_f32 v96, v75, v93, v115
	v_cvt_pk_bf16_f32 v95, v94, v93
	v_fma_f32 v97, v71, v94, v123
	v_fma_f32 v94, v70, v94, v96
	v_fma_f32 v93, v70, v93, v97
	v_cvt_pk_bf16_f32 v96, v94, v93
	ds_write2_b32 v91, v95, v96 offset0:184 offset1:252
	s_waitcnt lgkmcnt(0)
	s_barrier
	s_and_saveexec_b64 s[4:5], vcc
	v_add_u32_e32 v95, v84, v85
	s_waitcnt vmcnt(3)
	ds_write_b128 v95, v[64:67] offset:29696
	s_or_b64 exec, exec, s[4:5]
	s_add_i32 s4, s10, 6
	s_min_u32 s5, s4, 0x10a
	s_lshl_b32 s5, s5, 4
	s_cmp_lt_u32 s4, 11
	s_movk_i32 s4, 0xff50
	s_movk_i32 s11, 0xaf
	s_cselect_b32 s4, 0x50, s4
	s_cselect_b32 s11, s11, 0x10af
	s_cselect_b32 s12, s8, s2
	s_add_i32 s13, s5, s4
	s_sub_i32 s11, s11, s5
	s_and_b64 s[4:5], s[6:7], exec
	s_cselect_b32 s4, s13, s11
	s_add_i32 s4, s4, s12
	v_add_u32_e32 v64, s4, v74
	v_mad_u32_u24 v64, v64, s63, v82
	v_ashrrev_i32_e32 v65, 31, v64
	v_lshl_add_u64 v[64:65], v[64:65], 1, s[82:83]
	global_load_dwordx4 v[64:67], v[64:65], off
	ds_read_b128 v[96:99], v83 offset:15360
	ds_read_b128 v[100:103], v83 offset:15376
	ds_read_b128 v[104:107], v83 offset:10240
	ds_read_b128 v[108:111], v83 offset:10256
	ds_read_b128 v[112:115], v83 offset:10272
	ds_read_b128 v[116:119], v83 offset:10288
	ds_read_b128 v[120:123], v83 offset:15392
	ds_read_b128 v[124:127], v83 offset:15408
	s_waitcnt lgkmcnt(7)
	v_fma_f32 v96, v71, v94, v96
	s_waitcnt lgkmcnt(5)
	v_fma_f32 v95, v75, v93, v104
	s_waitcnt lgkmcnt(0)
	s_add_i32 s10, s10, 7
	v_fma_f32 v94, v70, v94, v95
	v_fma_f32 v93, v70, v93, v96
	s_cmpk_gt_u32 s10, 0x10e
	v_fma_f32 v96, v75, v93, v105
	v_cvt_pk_bf16_f32 v95, v94, v93
	v_fma_f32 v97, v71, v94, v97
	v_fma_f32 v94, v70, v94, v96
	v_fma_f32 v93, v70, v93, v97
	v_cvt_pk_bf16_f32 v96, v94, v93
	ds_write2_b32 v88, v95, v96 offset0:64 offset1:132
	v_fma_f32 v96, v71, v94, v98
	v_fma_f32 v95, v75, v93, v106
	v_fma_f32 v94, v70, v94, v95
	v_fma_f32 v93, v70, v93, v96
	v_fma_f32 v96, v75, v93, v107
	v_cvt_pk_bf16_f32 v95, v94, v93
	v_fma_f32 v97, v71, v94, v99
	v_fma_f32 v94, v70, v94, v96
	v_fma_f32 v93, v70, v93, v97
	v_cvt_pk_bf16_f32 v96, v94, v93
	ds_write2_b32 v86, v95, v96 offset0:72 offset1:140
	v_fma_f32 v96, v71, v94, v100
	s_waitcnt lgkmcnt(6)
	v_fma_f32 v95, v75, v93, v108
	v_fma_f32 v94, v70, v94, v95
	v_fma_f32 v93, v70, v93, v96
	v_fma_f32 v96, v75, v93, v109
	v_cvt_pk_bf16_f32 v95, v94, v93
	v_fma_f32 v97, v71, v94, v101
	v_fma_f32 v94, v70, v94, v96
	v_fma_f32 v93, v70, v93, v97
	v_cvt_pk_bf16_f32 v96, v94, v93
	ds_write2_b32 v81, v95, v96 offset0:80 offset1:148
	v_fma_f32 v96, v71, v94, v102
	v_fma_f32 v95, v75, v93, v110
	v_fma_f32 v94, v70, v94, v95
	v_fma_f32 v93, v70, v93, v96
	v_fma_f32 v96, v75, v93, v111
	v_cvt_pk_bf16_f32 v95, v94, v93
	v_fma_f32 v97, v71, v94, v103
	v_fma_f32 v94, v70, v94, v96
	v_fma_f32 v93, v70, v93, v97
	v_cvt_pk_bf16_f32 v96, v94, v93
	ds_write2_b32 v80, v95, v96 offset0:88 offset1:156
	s_waitcnt lgkmcnt(5)
	v_fma_f32 v96, v71, v94, v120
	v_fma_f32 v95, v75, v93, v112
	v_fma_f32 v94, v70, v94, v95
	v_fma_f32 v93, v70, v93, v96
	v_fma_f32 v96, v75, v93, v113
	v_cvt_pk_bf16_f32 v95, v94, v93
	v_fma_f32 v97, v71, v94, v121
	v_fma_f32 v94, v70, v94, v96
	v_fma_f32 v93, v70, v93, v97
	v_cvt_pk_bf16_f32 v96, v94, v93
	ds_write2_b32 v79, v95, v96 offset0:96 offset1:164
	v_fma_f32 v96, v71, v94, v122
	v_fma_f32 v95, v75, v93, v114
	v_fma_f32 v94, v70, v94, v95
	v_fma_f32 v93, v70, v93, v96
	v_fma_f32 v96, v75, v93, v115
	v_cvt_pk_bf16_f32 v95, v94, v93
	v_fma_f32 v97, v71, v94, v123
	v_fma_f32 v94, v70, v94, v96
	v_fma_f32 v93, v70, v93, v97
	v_cvt_pk_bf16_f32 v96, v94, v93
	ds_write2_b32 v78, v95, v96 offset0:104 offset1:172
	s_waitcnt lgkmcnt(6)
	v_fma_f32 v96, v71, v94, v124
	v_fma_f32 v95, v75, v93, v116
	v_fma_f32 v94, v70, v94, v95
	v_fma_f32 v93, v70, v93, v96
	v_fma_f32 v96, v75, v93, v117
	v_cvt_pk_bf16_f32 v95, v94, v93
	v_fma_f32 v97, v71, v94, v125
	v_fma_f32 v94, v70, v94, v96
	v_fma_f32 v93, v70, v93, v97
	v_cvt_pk_bf16_f32 v96, v94, v93
	ds_write2_b32 v77, v95, v96 offset0:112 offset1:180
	v_fma_f32 v96, v71, v94, v126
	v_fma_f32 v95, v75, v93, v118
	v_fma_f32 v94, v70, v94, v95
	v_fma_f32 v93, v70, v93, v96
	v_fma_f32 v96, v75, v93, v119
	v_cvt_pk_bf16_f32 v95, v94, v93
	v_fma_f32 v97, v71, v94, v127
	v_fma_f32 v94, v70, v94, v96
	v_fma_f32 v93, v70, v93, v97
	v_cvt_pk_bf16_f32 v96, v94, v93
	ds_write2_b32 v76, v95, v96 offset0:120 offset1:188
	s_waitcnt lgkmcnt(0)
	s_barrier
	s_cbranch_scc1 .LBB0_373
	s_and_saveexec_b64 s[4:5], vcc
	s_cbranch_execz .LBB0_372
	v_add_u32_e32 v95, v84, v85
	s_waitcnt vmcnt(3)
	ds_write_b128 v95, v[60:63] offset:29184
	s_branch .LBB0_372
.LBB0_385:
	s_waitcnt vmcnt(2)
	ds_read_b128 v[52:55], v83 offset:15360
	s_waitcnt vmcnt(1)
	ds_read_b128 v[56:59], v83 offset:15376
	s_waitcnt vmcnt(0)
	ds_read_b128 v[60:63], v83 offset:10240
	ds_read_b128 v[64:67], v83 offset:10256
	ds_read_b128 v[92:95], v83 offset:10272
	ds_read_b128 v[96:99], v83 offset:10288
	ds_read_b128 v[100:103], v83 offset:15392
	ds_read_b128 v[82:85], v83 offset:15408
	s_waitcnt lgkmcnt(5)
	v_fma_f32 v60, v75, v90, v60
	v_fma_f32 v52, v71, v89, v52
	s_waitcnt lgkmcnt(0)
	v_fma_f32 v60, v70, v89, v60
	v_fma_f32 v52, v70, v90, v52
	v_fma_f32 v53, v71, v60, v53
	v_cvt_pk_bf16_f32 v87, v60, v52
	v_fma_f32 v61, v75, v52, v61
	v_fma_f32 v52, v70, v52, v53
	v_fma_f32 v60, v70, v60, v61
	v_cvt_pk_bf16_f32 v53, v60, v52
	ds_write2_b32 v88, v87, v53 offset0:64 offset1:132
	v_fma_f32 v53, v75, v52, v62
	v_fma_f32 v54, v71, v60, v54
	v_fma_f32 v53, v70, v60, v53
	v_fma_f32 v52, v70, v52, v54
	v_fma_f32 v55, v71, v53, v55
	v_cvt_pk_bf16_f32 v54, v53, v52
	v_fma_f32 v60, v75, v52, v63
	v_fma_f32 v52, v70, v52, v55
	v_fma_f32 v53, v70, v53, v60
	v_cvt_pk_bf16_f32 v55, v53, v52
	ds_write2_b32 v86, v54, v55 offset0:72 offset1:140
	v_fma_f32 v55, v71, v53, v56
	s_waitcnt lgkmcnt(6)
	v_fma_f32 v54, v75, v52, v64
	v_fma_f32 v53, v70, v53, v54
	v_fma_f32 v52, v70, v52, v55
	v_fma_f32 v55, v75, v52, v65
	v_cvt_pk_bf16_f32 v54, v53, v52
	v_fma_f32 v56, v71, v53, v57
	v_fma_f32 v53, v70, v53, v55
	v_fma_f32 v52, v70, v52, v56
	v_cvt_pk_bf16_f32 v55, v53, v52
	ds_write2_b32 v81, v54, v55 offset0:80 offset1:148
	v_fma_f32 v55, v71, v53, v58
	v_fma_f32 v54, v75, v52, v66
	v_fma_f32 v53, v70, v53, v54
	v_fma_f32 v52, v70, v52, v55
	v_fma_f32 v55, v75, v52, v67
	v_cvt_pk_bf16_f32 v54, v53, v52
	v_fma_f32 v56, v71, v53, v59
	v_fma_f32 v53, v70, v53, v55
	v_fma_f32 v52, v70, v52, v56
	v_cvt_pk_bf16_f32 v55, v53, v52
	ds_write2_b32 v80, v54, v55 offset0:88 offset1:156
	s_waitcnt lgkmcnt(5)
	v_fma_f32 v55, v71, v53, v100
	v_fma_f32 v54, v75, v52, v92
	v_fma_f32 v53, v70, v53, v54
	v_fma_f32 v52, v70, v52, v55
	v_fma_f32 v55, v75, v52, v93
	v_cvt_pk_bf16_f32 v54, v53, v52
	v_fma_f32 v56, v71, v53, v101
	v_fma_f32 v53, v70, v53, v55
	v_fma_f32 v52, v70, v52, v56
	v_cvt_pk_bf16_f32 v55, v53, v52
	ds_write2_b32 v79, v54, v55 offset0:96 offset1:164
	v_fma_f32 v55, v71, v53, v102
	v_fma_f32 v54, v75, v52, v94
	v_fma_f32 v53, v70, v53, v54
	v_fma_f32 v52, v70, v52, v55
	v_fma_f32 v55, v75, v52, v95
	v_cvt_pk_bf16_f32 v54, v53, v52
	v_fma_f32 v56, v71, v53, v103
	v_fma_f32 v53, v70, v53, v55
	v_fma_f32 v52, v70, v52, v56
	v_cvt_pk_bf16_f32 v55, v53, v52
	ds_write2_b32 v78, v54, v55 offset0:104 offset1:172
	s_waitcnt lgkmcnt(6)
	v_fma_f32 v55, v71, v53, v82
	v_fma_f32 v54, v75, v52, v96
	v_fma_f32 v53, v70, v53, v54
	v_fma_f32 v52, v70, v52, v55
	v_fma_f32 v55, v75, v52, v97
	v_cvt_pk_bf16_f32 v54, v53, v52
	v_fma_f32 v56, v71, v53, v83
	v_fma_f32 v53, v70, v53, v55
	v_fma_f32 v52, v70, v52, v56
	v_cvt_pk_bf16_f32 v55, v53, v52
	ds_write2_b32 v77, v54, v55 offset0:112 offset1:180
	v_fma_f32 v54, v75, v52, v98
	v_fma_f32 v55, v71, v53, v84
	v_fma_f32 v52, v70, v52, v55
	v_fma_f32 v53, v70, v53, v54
	v_cvt_pk_bf16_f32 v54, v53, v52
	v_fma_f32 v55, v75, v52, v99
	v_fma_f32 v56, v71, v53, v85
	v_fma_f32 v52, v70, v52, v56
	v_fma_f32 v53, v70, v53, v55
	v_cvt_pk_bf16_f32 v52, v53, v52
	ds_write2_b32 v76, v54, v52 offset0:120 offset1:188
	s_waitcnt lgkmcnt(0)
	s_barrier
	s_barrier
	s_setprio 0
	s_mov_b64 s[4:5], 0

.LBB0_388:
	v_add_u32_e32 v177, s14, v74
	v_lshl_or_b32 v180, v177, 10, v58
	s_nop 2
	v_cvt_pk_bf16_f32 v52, v172, v173
	v_cvt_pk_bf16_f32 v53, v174, v175
	v_lshl_add_u64 v[54:55], v[180:181], 1, s[10:11]
	global_store_dwordx2 v[54:55], v[52:53], off offset:1536

.LBB0_390:
	s_cmp_lt_u32 s2, 2
	s_cbranch_scc1 .Ls5a_x
	s_bitcmp1_b32 s2, 0
	s_cselect_b32 s4, 0x1100, 0
	v_add_u32_e32 v176, s4, v57
	ds_read_b128 v[128:131], v176 offset:20480
	ds_read_b128 v[132:135], v176 offset:20544
	ds_read_b128 v[136:139], v176 offset:20608
	ds_read_b128 v[140:143], v176 offset:20672
.Ls5a_x:
	s_cmpk_gt_u32 s2, 0x10f
	s_cbranch_scc1 .Ls5a_y
	s_and_b32 s4, s2, 1
	v_lshl_add_u32 v52, s4, 9, v56
	ds_read_b128 v[52:55], v52 offset:29184
	s_mulk_i32 s4, 0x2800
	v_add_u32_e32 v64, s4, v59
	s_waitcnt lgkmcnt(0)
	v_cndmask_b32_e64 v55, v55, 0, s[8:9]
	v_cndmask_b32_e64 v54, v54, 0, s[8:9]
	v_cndmask_b32_e64 v53, v53, 0, s[8:9]
	v_cndmask_b32_e64 v52, v52, 0, s[8:9]
	s_nop 1
	v_mfma_f32_16x16x32_bf16 v[60:63], v[52:55], v[8:11], 0
	v_mfma_f32_16x16x32_bf16 v[144:147], v[52:55], v[4:7], 0
	v_mfma_f32_16x16x32_bf16 v[148:151], v[52:55], v[16:19], 0
	v_mfma_f32_16x16x32_bf16 v[152:155], v[52:55], v[12:15], 0
	v_mfma_f32_16x16x32_bf16 v[156:159], v[52:55], v[24:27], 0
	v_mfma_f32_16x16x32_bf16 v[160:163], v[52:55], v[20:23], 0
	v_mfma_f32_16x16x32_bf16 v[164:167], v[52:55], v[32:35], 0
	v_mfma_f32_16x16x32_bf16 v[168:171], v[52:55], v[28:31], 0
.Ls5a_y:
	s_cmp_lt_u32 s2, 2
	s_cbranch_scc1 .Ls5a_w
	s_waitcnt lgkmcnt(0)
	v_mfma_f32_16x16x32_bf16 v[172:175], v[36:39], v[128:131], 0
	v_mfma_f32_16x16x32_bf16 v[172:175], v[40:43], v[132:135], v[172:175]
	v_mfma_f32_16x16x32_bf16 v[172:175], v[44:47], v[136:139], v[172:175]
	v_mfma_f32_16x16x32_bf16 v[172:175], v[48:51], v[140:143], v[172:175]
.Ls5a_w:
	s_cmpk_gt_u32 s2, 0x10f
	s_cbranch_scc1 .Ls5a_t
	s_nop 1
	ds_write_b128 v64, v[60:63]
	ds_write_b128 v64, v[144:147] offset:1280
	ds_write_b128 v64, v[148:151] offset:2560
	ds_write_b128 v64, v[152:155] offset:3840
	ds_write_b128 v64, v[156:159] offset:5120
	ds_write_b128 v64, v[160:163] offset:6400
	ds_write_b128 v64, v[164:167] offset:7680
	ds_write_b128 v64, v[168:171] offset:8960
.Ls5a_t:
	s_cmp_lt_u32 s2, 2
	s_cbranch_scc1 .LBB0_389
	s_mov_b64 s[4:5], -1
	s_cmp_gt_u32 s2, 17
	s_cbranch_scc0 .LBB0_395
	s_and_b64 s[4:5], s[6:7], exec
	s_cselect_b32 s4, s13, s12
	s_add_i32 s14, s1, s4
	s_mov_b64 s[4:5], 0

.LBB0_428:
	s_and_saveexec_b64 s[4:5], s[6:7]
	s_cbranch_execz .LBB0_430
	s_waitcnt vmcnt(6)
	ds_write2st64_b32 v60, v55, v58 offset1:1

.LBB0_440:
	s_add_i32 s48, s45, 1
	s_cmpk_lt_u32 s48, 0x43
	s_cselect_b64 s[34:35], -1, 0
	s_and_b64 s[50:51], s[6:7], s[34:35]
	s_and_saveexec_b64 s[4:5], s[50:51]
	s_cbranch_execz .LBB0_442
	s_waitcnt vmcnt(6)
	ds_write2st64_b32 v90, v56, v57 offset1:1

.Lgdn_skipA:
	s_waitcnt vmcnt(0)
	s_branch .LBB0_440
